# mlstm2: parallel K-tile loads, pipelined S-stage LDS reads, gate vectors read from GV (computed once in mp_phase) instead of recomputed; mp_phase trimmed to its consumed outputs
# speedup vs baseline: 1.0235x; 1.0235x over previous
; __device__ void mp_phase(const Params& p, unsigned char* smem) {
;     ...
;     for (int unit = blockIdx.x; unit < 1024; unit += gridDim.x) {
;         const int chunk = unit & 31, bh = unit >> 5, h = bh & 7, b = bh >> 3, row0 = b * SEQL + chunk * 128;
; #pragma unroll
;         for (int i = 0; i < 8; ++i) { const int idx = tid + 512 * i, r = idx >> 5, cc = (idx & 31) * 8;
;             *(u32x4*)(Qs + r * 264 + cc) = *(const u32x4*)(Q + (size_t)(row0 + r) * 2048 + 256 * h + cc);
;             *(u32x4*)(Ks + r * 264 + cc) = *(const u32x4*)(KX + (size_t)(row0 + r) * 2048 + 256 * h + cc); }
.LBB0_380:
	s_lshl_b32 s18, s24, 4
	s_lshl_b32 s25, s24, 7
	s_and_b32 s18, s18, 0xfffff000
	s_and_b32 s25, s25, 0xf80
	s_or_b32 s29, s18, s25
	s_bfe_u32 s28, s24, 0x30005
	v_or_b32_e32 v2, s29, v22
	v_or_b32_e32 v54, s29, v25
	v_or_b32_e32 v62, s29, v28
	v_or_b32_e32 v70, s29, v30
	v_or_b32_e32 v78, s29, v33
	v_or_b32_e32 v86, s29, v35
	v_or_b32_e32 v94, s29, v38
	v_add_u32_e32 v106, s29, v40
	s_lshl_b32 s18, s28, 9
	v_ashrrev_i32_e32 v3, 31, v2
	v_ashrrev_i32_e32 v55, 31, v54
	v_ashrrev_i32_e32 v63, 31, v62
	v_ashrrev_i32_e32 v71, 31, v70
	v_ashrrev_i32_e32 v79, 31, v78
	v_ashrrev_i32_e32 v87, 31, v86
	v_ashrrev_i32_e32 v95, 31, v94
	v_ashrrev_i32_e32 v107, 31, v106
	v_lshl_add_u64 v[102:103], v[8:9], 0, s[18:19]
	v_lshl_add_u64 v[104:105], v[10:11], 0, s[18:19]
	v_lshlrev_b64 v[2:3], 12, v[2:3]
	v_lshlrev_b64 v[54:55], 12, v[54:55]
	v_lshlrev_b64 v[62:63], 12, v[62:63]
	v_lshlrev_b64 v[70:71], 12, v[70:71]
	v_lshlrev_b64 v[78:79], 12, v[78:79]
	v_lshlrev_b64 v[86:87], 12, v[86:87]
	v_lshlrev_b64 v[94:95], 12, v[94:95]
	v_lshlrev_b64 v[106:107], 12, v[106:107]
	v_lshl_add_u64 v[4:5], v[102:103], 0, v[2:3]
	v_lshl_add_u64 v[50:51], v[104:105], 0, v[2:3]
	v_lshl_add_u64 v[56:57], v[102:103], 0, v[54:55]
	v_lshl_add_u64 v[58:59], v[104:105], 0, v[54:55]
	v_lshl_add_u64 v[64:65], v[102:103], 0, v[62:63]
	v_lshl_add_u64 v[66:67], v[104:105], 0, v[62:63]
	v_lshl_add_u64 v[72:73], v[102:103], 0, v[70:71]
	v_lshl_add_u64 v[74:75], v[104:105], 0, v[70:71]
	v_lshl_add_u64 v[80:81], v[102:103], 0, v[78:79]
	v_lshl_add_u64 v[82:83], v[104:105], 0, v[78:79]
	v_lshl_add_u64 v[88:89], v[102:103], 0, v[86:87]
	v_lshl_add_u64 v[90:91], v[104:105], 0, v[86:87]
	v_lshl_add_u64 v[96:97], v[102:103], 0, v[94:95]
	v_lshl_add_u64 v[98:99], v[104:105], 0, v[94:95]
	v_lshl_add_u64 v[102:103], v[102:103], 0, v[106:107]
	v_lshl_add_u64 v[106:107], v[104:105], 0, v[106:107]
	s_and_b64 vcc, exec, s[14:15]
	s_mov_b64 s[26:27], -1
	s_cbranch_vccnz .LBB0_382
	s_ashr_i32 s25, s24, 31
	s_mov_b64 s[26:27], 0

; __device__ __forceinline__ u16 f2bf(float f) { return (u16)(pk2(f, 0.f) & 0xffffu); }
; #define MFMA16(a, b, c) __builtin_amdgcn_mfma_f32_16x16x32_bf16((a), (b), (c), 0, 0, 0)
; __device__ void mp_phase(const Params& p, unsigned char* smem) {
;     ...
;         __syncthreads();
;         u16* pp = PP + (size_t)unit * (128 * 128);
;         for (int i = wave; i < 36; i += 8) {
;             int rb = 0, base = 0; while (base + rb + 1 <= i) { base += rb + 1; ++rb; }
;             const int n = i - base;
;             f32x4 acc = {0.f, 0.f, 0.f, 0.f};
; #pragma unroll
;             for (int ks = 0; ks < 8; ++ks) { const bf16x8 af = *(const bf16x8*)(Qs + (16 * rb + l15) * 264 + 32 * ks + 8 * lq), bf_ = *(const bf16x8*)(Ks + (16 * n + l15) * 264 + 32 * ks + 8 * lq);
;                 acc = MFMA16(af, bf_, acc); }
;             const int s = 16 * n + l15; const float cs = gc[s];
; #pragma unroll
;             for (int r = 0; r < 4; ++r) { const int t = 16 * rb + 4 * lq + r; const float val = (s <= t) ? acc[r] * __expf(cs - gMp[t]) : 0.f; pp[t * 128 + s] = f2bf(val); }
;         }
;         if (wave < 4) { const int rb = 2 * wave, n = rb + 1;
; #pragma unroll
;             for (int r = 0; r < 4; ++r) pp[(16 * rb + 4 * lq + r) * 128 + 16 * n + l15] = 0; }
;         __syncthreads();
.LBB0_384:
	s_lshl_b64 s[26:27], s[24:25], 15
	s_add_u32 s26, s31, s26
	s_addc_u32 s27, s33, s27
	s_andn2_b64 vcc, exec, s[20:21]
	s_mov_b32 s18, s30
	s_waitcnt lgkmcnt(0)
	s_barrier
	s_branch .LBB0_379

; __device__ void mlstm2_phase(const Params& p, unsigned char* smem) {
;     ...
;     for (int unit = blockIdx.x; unit < 256; unit += gridDim.x) {
;         int sl = unit & 7, bh_ = unit >> 3;
;         if (gridDim.x == 256) { const int xcd_ = unit & 7, j_ = unit >> 3; bh_ = xcd_ * 4 + (j_ >> 3); sl = j_ & 7; }
;         const int h = bh_ & 7, b = bh_ >> 3;
;         f32x4 accC[3][2];
; #pragma unroll
;         for (int a = 0; a < 3; ++a)
; #pragma unroll
;             for (int c = 0; c < 2; ++c) accC[a][c] = (f32x4){0.f, 0.f, 0.f, 0.f};
;         for (int e = tid; e < 16 * 136; e += 512) { const int r = e / 136; Vt[32 * 136 + e] = (r == 0) ? (u16)0x3F80 : (u16)0; Vwt[32 * 136 + e] = 0; }
;         for (int e = tid; e < 48 * 264; e += 512) Ct[e] = 0;
;         if (tid == 0) gS[1] = 0.f;
;         const int vc = 256 * h + 32 * sl + 4 * (tid & 7);
;         const float* wvp = p.in[14] + (size_t)(vc >> 2) * 16;
;         __syncthreads();
.LBB0_418:
	v_add_u32_e32 v3, 0x200, v3
	s_movk_i32 s26, 0x2f7f
	v_cmp_lt_u32_e32 vcc, s26, v3
	ds_write_b16 v2, v93
	s_or_b64 s[52:53], vcc, s[52:53]
	v_add_u32_e32 v2, 0x400, v2
	s_andn2_b64 exec, exec, s[52:53]
	s_cbranch_execnz .LBB0_418
	s_or_b64 exec, exec, s[52:53]
	s_and_saveexec_b64 s[52:53], s[2:3]
	v_mov_b32_e32 v2, s33
	ds_write_b32 v2, v93
	s_or_b64 exec, exec, s[52:53]
	s_and_b32 s26, s28, 7
	s_ashr_i32 s27, s28, 3
	v_writelane_b32 v250, s28, 43
	s_ashr_i32 s52, s28, 6
	s_lshl_b32 s53, s26, 2
	v_readlane_b32 s28, v251, 45
	s_add_i32 s54, s53, s52
	v_readlane_b32 s29, v251, 46
	s_and_b64 s[52:53], s[28:29], exec
	s_cselect_b32 s54, s54, s27
	s_and_b32 s55, s54, 7
	s_and_b32 s27, s27, 7
	s_and_b64 s[52:53], s[28:29], exec
	s_cselect_b32 s26, s27, s26
	v_lshl_or_b32 v2, s26, 5, v110
	v_lshl_or_b32 v2, s55, 8, v2
	v_lshlrev_b32_e32 v92, 4, v2
	v_readlane_b32 s28, v251, 43
	v_readlane_b32 s52, v251, 32
	v_lshl_add_u64 v[100:101], s[80:81], 0, v[92:93]
	s_lshl_b32 s30, s55, 9
	v_lshlrev_b32_e32 v92, 1, v2
	v_readlane_b32 s29, v251, 44
	v_readlane_b32 s53, v251, 33
	v_lshl_add_u64 v[102:103], v[94:95], 0, s[30:31]
	v_lshl_add_u64 v[104:105], v[96:97], 0, s[30:31]
	v_lshl_add_u64 v[106:107], s[28:29], 0, v[92:93]
	s_mov_b64 s[56:57], s[30:31]
	s_load_dwordx4 s[28:31], s[52:53], 0x150
	s_lshl_b32 s27, s54, 9
	s_and_b32 s27, s27, 0xfffff000
	s_waitcnt lgkmcnt(0)
	s_mul_i32 s98, s54, 0xc000
	s_add_u32 s98, s28, s98
	s_addc_u32 s99, s29, 0
	s_add_u32 s98, s98, 0x1fa00000
	s_addc_u32 s99, s99, 0
	s_mov_b64 s[30:31], s[56:57]
	v_mov_b32_e32 v2, 0
	s_add_u32 s52, s28, s30
	s_addc_u32 s53, s29, 0
	s_lshl_b32 s26, s26, 6
	s_add_u32 s52, s52, s26
	s_addc_u32 s53, s53, 0
	s_lshl_b32 s26, s55, 2
	v_readlane_b32 s28, v250, 35
	s_add_u32 s88, s28, s26
	v_readlane_b32 s26, v250, 36
	v_lshl_add_u64 v[108:109], v[90:91], 1, s[52:53]
	s_addc_u32 s89, s26, 0
	v_or_b32_e32 v92, s27, v112
	v_add_u32_e32 v230, s27, v122
	v_or_b32_e32 v231, s27, v131
	v_or_b32_e32 v232, s27, v130
	v_add_u32_e32 v233, s27, v111
	v_or_b32_e32 v234, s27, v129
	v_or_b32_e32 v235, s27, v125
	v_or_b32_e32 v236, s27, v128
	v_or_b32_e32 v237, s27, v127
	v_or_b32_e32 v238, s27, v126
	s_mov_b32 s79, 0
	v_mov_b32_e32 v3, v2
	v_mov_b32_e32 v4, v2
	v_mov_b32_e32 v5, v2
	v_mov_b32_e32 v6, v2
	v_mov_b32_e32 v7, v2
	v_mov_b32_e32 v8, v2
	v_mov_b32_e32 v9, v2
	v_mov_b32_e32 v10, v2
	v_mov_b32_e32 v11, v2
	v_mov_b32_e32 v12, v2
	v_mov_b32_e32 v13, v2
	v_mov_b32_e32 v14, v2
	v_mov_b32_e32 v15, v2
	v_mov_b32_e32 v16, v2
	v_mov_b32_e32 v17, v2
	v_mov_b32_e32 v18, v2
	v_mov_b32_e32 v19, v2
	v_mov_b32_e32 v20, v2
	v_mov_b32_e32 v21, v2
	v_mov_b32_e32 v22, v2
	v_mov_b32_e32 v23, v2
	v_mov_b32_e32 v24, v2
	v_mov_b32_e32 v25, v2
	s_barrier
	s_branch .LBB0_423

; __device__ void mlstm2_phase(const Params& p, unsigned char* smem) {
;     ...
;         for (int chunk = 0; chunk < 32; ++chunk) {
;             const int row0 = b * SEQL + chunk * 128, cu = bh_ * 32 + chunk;
; #pragma unroll
;             for (int i = 0; i < 8; ++i) { const int idx = tid + 512 * i, r = idx >> 5, cc = (idx & 31) * 8;
;                 *(u32x4*)(Ks + r * 264 + cc) = *(const u32x4*)(KX + (size_t)(row0 + r) * 2048 + 256 * h + cc); }
;             bf16x8 qf[8];
; #pragma unroll
;             for (int ks = 0; ks < 8; ++ks) qf[ks] = *(const bf16x8*)(Q + (size_t)(row0 + 16 * wave + l15) * 2048 + 256 * h + 32 * ks + 8 * lq);
;             float vv[2][4];
; #pragma unroll
;             for (int i = 0; i < 2; ++i) { const int t = (tid + 512 * i) >> 3; const u32x2 raw = *(const u32x2*)(XM + (size_t)(row0 + t) * 2048 + vc);
;                 const float x0 = bflo(raw.x), x1 = bfhi(raw.x), x2 = bflo(raw.y), x3 = bfhi(raw.y);
; #pragma unroll
;                 for (int jj = 0; jj < 4; ++jj) vv[i][jj] = x0 * wvp[jj] + x1 * wvp[4 + jj] + x2 * wvp[8 + jj] + x3 * wvp[12 + jj]; }
;             float m_new = 0.f;
;             const float* G = (const float*)(p.ws + OFF_G);
;             if (wave == 0) {
;                 const float m_prev = gS[1];
;                 const int t0 = 2 * lane;
;                 const float ig0 = G[(size_t)(row0 + t0) * 16 + h], fg0 = G[(size_t)(row0 + t0) * 16 + 8 + h];
;                 const float ig1 = G[(size_t)(row0 + t0 + 1) * 16 + h], fg1 = G[(size_t)(row0 + t0 + 1) * 16 + 8 + h];
;                 const float lf0 = -softplusf_(-fg0), lf1 = -softplusf_(-fg1);
;                 float s_ = lf0 + lf1;
; #pragma unroll
;                 for (int d = 1; d < 64; d <<= 1) { const float o = __shfl_up(s_, d); if (lane >= d) s_ += o; }
;                 const float b1 = s_, b0 = s_ - lf1;
;                 const float c0 = ig0 - b0, c1 = ig1 - b1;
;                 float mx = fmaxf(c0, c1);
; #pragma unroll
;                 for (int d = 1; d < 64; d <<= 1) { const float o = __shfl_up(mx, d); if (lane >= d) mx = fmaxf(mx, o); }
;                 float pm = __shfl_up(mx, 1); if (lane == 0) pm = -3.0e38f;
;                 const float M0p = fmaxf(pm, c0), M1p = mx;
;                 const float M0 = fmaxf(M0p, m_prev), M1 = fmaxf(M1p, m_prev);
;                 const float Ml = __shfl(M1, 63), bL = __shfl(b1, 63);
.LBB0_423:
	v_add_u32_e32 v30, s79, v235
	v_ashrrev_i32_e32 v31, 31, v30
	v_lshlrev_b64 v[26:27], 12, v[30:31]
	v_lshl_add_u64 v[26:27], v[102:103], 0, v[26:27]
	global_load_dwordx4 v[26:29], v[26:27], off
	v_add_u32_e32 v32, s79, v238
	v_ashrrev_i32_e32 v33, 31, v32
	v_lshlrev_b64 v[32:33], 12, v[32:33]
	v_lshl_add_u64 v[32:33], v[102:103], 0, v[32:33]
	global_load_dwordx4 v[32:35], v[32:33], off
	v_add_u32_e32 v36, 32, v30
	v_ashrrev_i32_e32 v37, 31, v36
	v_lshlrev_b64 v[36:37], 12, v[36:37]
	v_lshl_add_u64 v[36:37], v[102:103], 0, v[36:37]
	global_load_dwordx4 v[36:39], v[36:37], off
	v_add_u32_e32 v40, s79, v237
	v_ashrrev_i32_e32 v41, 31, v40
	v_lshlrev_b64 v[40:41], 12, v[40:41]
	v_lshl_add_u64 v[40:41], v[102:103], 0, v[40:41]
	global_load_dwordx4 v[40:43], v[40:41], off
	v_add_u32_e32 v44, 64, v30
	v_ashrrev_i32_e32 v45, 31, v44
	v_lshlrev_b64 v[44:45], 12, v[44:45]
	v_lshl_add_u64 v[44:45], v[102:103], 0, v[44:45]
	global_load_dwordx4 v[44:47], v[44:45], off
	v_add_u32_e32 v48, s79, v236
	v_ashrrev_i32_e32 v49, 31, v48
	v_lshlrev_b64 v[48:49], 12, v[48:49]
	v_lshl_add_u64 v[48:49], v[102:103], 0, v[48:49]
	global_load_dwordx4 v[48:51], v[48:49], off
	v_add_u32_e32 v52, 0x60, v30
	v_ashrrev_i32_e32 v53, 31, v52
	v_lshlrev_b64 v[52:53], 12, v[52:53]
	v_lshl_add_u64 v[52:53], v[102:103], 0, v[52:53]
	global_load_dwordx4 v[52:55], v[52:53], off
	v_add_u32_e32 v60, s79, v234
	v_ashrrev_i32_e32 v61, 31, v60
	v_lshlrev_b64 v[60:61], 12, v[60:61]
	v_lshl_add_u64 v[60:61], v[102:103], 0, v[60:61]
	global_load_dwordx4 v[60:63], v[60:61], off
	v_add_u32_e32 v58, s79, v232
	v_ashrrev_i32_e32 v59, 31, v58
	v_lshlrev_b64 v[58:59], 12, v[58:59]
	v_lshl_add_u64 v[58:59], v[106:107], 0, v[58:59]
	v_add_u32_e32 v74, s79, v231
	v_ashrrev_i32_e32 v75, 31, v74
	v_lshlrev_b64 v[74:75], 12, v[74:75]
	v_lshl_add_u64 v[74:75], v[106:107], 0, v[74:75]
	s_andn2_b64 vcc, exec, s[84:85]
	v_mov_b32_e32 v78, 0
	s_waitcnt vmcnt(7)
	ds_write_b128 v213, v[26:29]
	s_waitcnt vmcnt(6)
	ds_write_b128 v214, v[32:35]
	s_waitcnt vmcnt(5)
	ds_write_b128 v213, v[36:39] offset:16896
	s_waitcnt vmcnt(4)
	ds_write_b128 v215, v[40:43]
	s_waitcnt vmcnt(3)
	ds_write_b128 v213, v[44:47] offset:33792
	s_waitcnt vmcnt(2)
	ds_write_b128 v216, v[48:51]
	s_waitcnt vmcnt(1)
	ds_write_b128 v213, v[52:55] offset:50688
	s_waitcnt vmcnt(0)
	ds_write_b128 v217, v[60:63]
	v_add_u32_e32 v26, s79, v233
	v_ashrrev_i32_e32 v27, 31, v26
	v_lshlrev_b64 v[26:27], 12, v[26:27]
	v_lshl_add_u64 v[26:27], v[104:105], 0, v[26:27]
	global_load_dwordx4 v[54:57], v[26:27], off
	global_load_dwordx4 v[50:53], v[26:27], off offset:64
	global_load_dwordx4 v[46:49], v[26:27], off offset:128
	global_load_dwordx4 v[42:45], v[26:27], off offset:192
	global_load_dwordx4 v[38:41], v[26:27], off offset:256
	global_load_dwordx4 v[34:37], v[26:27], off offset:320
	global_load_dwordx4 v[30:33], v[26:27], off offset:384
	s_nop 0
	global_load_dwordx4 v[26:29], v[26:27], off offset:448
	s_nop 0
	global_load_dwordx2 v[76:77], v[58:59], off
	s_nop 0
	global_load_dwordx4 v[58:61], v[100:101], off offset:48
	global_load_dwordx4 v[62:65], v[100:101], off offset:32
	global_load_dwordx4 v[70:73], v[100:101], off offset:16
	global_load_dwordx4 v[66:69], v[100:101], off
	s_nop 0
	global_load_dwordx2 v[74:75], v[74:75], off
	s_cbranch_vccnz .LBB0_427
	v_mov_b32_e32 v78, s33
	ds_read_b32 v80, v78
	s_mul_i32 s30, s79, 12
	v_lshl_add_u32 v88, v112, 2, s30
	global_load_dwordx2 v[82:83], v88, s[98:99]
	global_load_dwordx2 v[84:85], v88, s[98:99] offset:512
	global_load_dwordx2 v[86:87], v88, s[98:99] offset:1024
	s_waitcnt vmcnt(0) lgkmcnt(0)
	ds_bpermute_b32 v81, v227, v83
	v_max_f32_e32 v88, v87, v87
	v_max_f32_e32 v78, v80, v80
	v_max_f32_e32 v79, v86, v78
	v_max_f32_e32 v99, v88, v78
	v_sub_f32_e32 v88, v86, v79
	v_sub_f32_e32 v89, v87, v99
	v_mul_f32_e32 v88, 0x3fb8aa3b, v88
	v_mul_f32_e32 v89, 0x3fb8aa3b, v89
	v_exp_f32_e32 v88, v88
	v_exp_f32_e32 v89, v89
	ds_write_b64 v113, v[88:89]
	ds_write_b64 v114, v[86:87]
	ds_write_b64 v115, v[84:85]
	v_sub_f32_e32 v86, v80, v79
	v_add_f32_e32 v79, v82, v79
	ds_bpermute_b32 v78, v227, v99
	v_mul_f32_e32 v79, 0xbfb8aa3b, v79
	v_exp_f32_e32 v82, v79
	v_add_f32_e32 v79, v83, v99
	v_mul_f32_e32 v79, 0xbfb8aa3b, v79
	v_exp_f32_e32 v83, v79
	s_waitcnt lgkmcnt(0)
	v_sub_f32_e32 v79, v84, v78
	v_mul_f32_e32 v79, 0x3fb8aa3b, v79
	v_sub_f32_e32 v87, v80, v99
	ds_write_b64 v117, v[82:83]
	v_exp_f32_e32 v82, v79
	v_sub_f32_e32 v79, v85, v78
	v_mul_f32_e32 v86, 0x3fb8aa3b, v86
	v_mul_f32_e32 v87, 0x3fb8aa3b, v87
	v_mul_f32_e32 v79, 0x3fb8aa3b, v79
	v_exp_f32_e32 v86, v86
	v_exp_f32_e32 v87, v87
	v_exp_f32_e32 v83, v79
	ds_write_b64 v116, v[86:87]
	ds_write_b64 v118, v[82:83]
	s_and_saveexec_b64 s[52:53], s[4:5]
	s_cbranch_execz .LBB0_426
	v_sub_f32_e32 v79, v80, v78
	v_mul_f32_e32 v79, 0x3fb8aa3b, v79
	v_exp_f32_e32 v79, v79
	v_mov_b32_e32 v80, s91
	ds_write_b32 v80, v79

; #define MFMA16(a, b, c) __builtin_amdgcn_mfma_f32_16x16x32_bf16((a), (b), (c), 0, 0, 0)
; __device__ void mlstm2_phase(const Params& p, unsigned char* smem) {
;     ...
;             { f32x4 accS[8];
; #pragma unroll
;               for (int n = 0; n < 8; ++n) { accS[n] = (f32x4){0.f, 0.f, 0.f, 0.f};
;                 if (n <= wave) {
; #pragma unroll
;                     for (int ks = 0; ks < 8; ++ks) { const bf16x8 kf = *(const bf16x8*)(Ks + (16 * n + l15) * 264 + 32 * ks + 8 * lq); accS[n] = MFMA16(qf[ks], kf, accS[n]); } } }
.LBB0_431:
	s_or_b64 exec, exec, s[52:53]
	ds_read_b128 v[240:243], v151
	ds_read_b128 v[244:247], v151 offset:64
	ds_read_b128 v[252:255], v151 offset:128
	ds_read_b128 v[58:61], v151 offset:192
	s_waitcnt lgkmcnt(3)
	v_mfma_f32_16x16x32_bf16 v[86:89], v[54:57], v[240:243], 0
	ds_read_b128 v[240:243], v151 offset:256
	s_waitcnt lgkmcnt(3)
	v_mfma_f32_16x16x32_bf16 v[86:89], v[50:53], v[244:247], v[86:89]
	ds_read_b128 v[244:247], v151 offset:320
	s_waitcnt lgkmcnt(3)
	v_mfma_f32_16x16x32_bf16 v[86:89], v[46:49], v[252:255], v[86:89]
	ds_read_b128 v[252:255], v151 offset:384
	s_waitcnt lgkmcnt(3)
	v_mfma_f32_16x16x32_bf16 v[86:89], v[42:45], v[58:61], v[86:89]
	ds_read_b128 v[58:61], v151 offset:448
	s_waitcnt lgkmcnt(3)
	v_mfma_f32_16x16x32_bf16 v[86:89], v[38:41], v[240:243], v[86:89]
	s_waitcnt lgkmcnt(2)
	v_mfma_f32_16x16x32_bf16 v[86:89], v[34:37], v[244:247], v[86:89]
	s_waitcnt lgkmcnt(1)
	v_mfma_f32_16x16x32_bf16 v[86:89], v[30:33], v[252:255], v[86:89]
	s_waitcnt lgkmcnt(0)
	v_mfma_f32_16x16x32_bf16 v[86:89], v[26:29], v[58:61], v[86:89]
	s_andn2_b64 vcc, exec, s[86:87]
	v_mov_b32_e32 v82, 0
	v_mov_b32_e32 v83, 0
	v_mov_b32_e32 v84, 0
	v_mov_b32_e32 v85, 0
	s_cbranch_vccnz .LBB0_433
	ds_read_b128 v[240:243], v151 offset:8448
	ds_read_b128 v[244:247], v151 offset:8512
	ds_read_b128 v[252:255], v151 offset:8576
	ds_read_b128 v[58:61], v151 offset:8640
	s_waitcnt lgkmcnt(3)
	v_mfma_f32_16x16x32_bf16 v[82:85], v[54:57], v[240:243], 0
	ds_read_b128 v[240:243], v151 offset:8704
	s_waitcnt lgkmcnt(3)
	v_mfma_f32_16x16x32_bf16 v[82:85], v[50:53], v[244:247], v[82:85]
	ds_read_b128 v[244:247], v151 offset:8768
	s_waitcnt lgkmcnt(3)
	v_mfma_f32_16x16x32_bf16 v[82:85], v[46:49], v[252:255], v[82:85]
	ds_read_b128 v[252:255], v151 offset:8832
	s_waitcnt lgkmcnt(3)
	v_mfma_f32_16x16x32_bf16 v[82:85], v[42:45], v[58:61], v[82:85]
	ds_read_b128 v[58:61], v151 offset:8896
	s_waitcnt lgkmcnt(3)
	v_mfma_f32_16x16x32_bf16 v[82:85], v[38:41], v[240:243], v[82:85]
	s_waitcnt lgkmcnt(2)
	v_mfma_f32_16x16x32_bf16 v[82:85], v[34:37], v[244:247], v[82:85]
	s_waitcnt lgkmcnt(1)
	v_mfma_f32_16x16x32_bf16 v[82:85], v[30:33], v[252:255], v[82:85]
	s_waitcnt lgkmcnt(0)
	v_mfma_f32_16x16x32_bf16 v[82:85], v[26:29], v[58:61], v[82:85]
.LBB0_433:
	s_nop 4
	v_cndmask_b32_e64 v58, 0, 1, s[96:97]
	v_cmp_ne_u32_e64 s[52:53], 1, v58
	s_andn2_b64 vcc, exec, s[96:97]
	v_mov_b32_e32 v78, 0
	v_mov_b32_e32 v79, 0
	v_mov_b32_e32 v80, 0
	v_mov_b32_e32 v81, 0
	s_cbranch_vccnz .LBB0_435
	ds_read_b128 v[240:243], v151 offset:16896
	ds_read_b128 v[244:247], v151 offset:16960
	ds_read_b128 v[252:255], v151 offset:17024
	ds_read_b128 v[58:61], v151 offset:17088
	s_waitcnt lgkmcnt(3)
	v_mfma_f32_16x16x32_bf16 v[78:81], v[54:57], v[240:243], 0
	ds_read_b128 v[240:243], v151 offset:17152
	s_waitcnt lgkmcnt(3)
	v_mfma_f32_16x16x32_bf16 v[78:81], v[50:53], v[244:247], v[78:81]
	ds_read_b128 v[244:247], v151 offset:17216
	s_waitcnt lgkmcnt(3)
	v_mfma_f32_16x16x32_bf16 v[78:81], v[46:49], v[252:255], v[78:81]
	ds_read_b128 v[252:255], v151 offset:17280
	s_waitcnt lgkmcnt(3)
	v_mfma_f32_16x16x32_bf16 v[78:81], v[42:45], v[58:61], v[78:81]
	ds_read_b128 v[58:61], v151 offset:17344
	s_waitcnt lgkmcnt(3)
	v_mfma_f32_16x16x32_bf16 v[78:81], v[38:41], v[240:243], v[78:81]
	s_waitcnt lgkmcnt(2)
	v_mfma_f32_16x16x32_bf16 v[78:81], v[34:37], v[244:247], v[78:81]
	s_waitcnt lgkmcnt(1)
	v_mfma_f32_16x16x32_bf16 v[78:81], v[30:33], v[252:255], v[78:81]
	s_waitcnt lgkmcnt(0)
	v_mfma_f32_16x16x32_bf16 v[78:81], v[26:29], v[58:61], v[78:81]
.LBB0_435:
	s_andn2_b64 vcc, exec, s[94:95]
	v_mov_b32_e32 v62, 0
	v_mov_b32_e32 v63, 0
	v_mov_b32_e32 v64, 0
	v_mov_b32_e32 v65, 0
	s_cbranch_vccnz .LBB0_437
	ds_read_b128 v[240:243], v151 offset:25344
	ds_read_b128 v[244:247], v151 offset:25408
	ds_read_b128 v[252:255], v151 offset:25472
	ds_read_b128 v[58:61], v151 offset:25536
	s_waitcnt lgkmcnt(3)
	v_mfma_f32_16x16x32_bf16 v[62:65], v[54:57], v[240:243], 0
	ds_read_b128 v[240:243], v151 offset:25600
	s_waitcnt lgkmcnt(3)
	v_mfma_f32_16x16x32_bf16 v[62:65], v[50:53], v[244:247], v[62:65]
	ds_read_b128 v[244:247], v151 offset:25664
	s_waitcnt lgkmcnt(3)
	v_mfma_f32_16x16x32_bf16 v[62:65], v[46:49], v[252:255], v[62:65]
	ds_read_b128 v[252:255], v151 offset:25728
	s_waitcnt lgkmcnt(3)
	v_mfma_f32_16x16x32_bf16 v[62:65], v[42:45], v[58:61], v[62:65]
	ds_read_b128 v[58:61], v151 offset:25792
	s_waitcnt lgkmcnt(3)
	v_mfma_f32_16x16x32_bf16 v[62:65], v[38:41], v[240:243], v[62:65]
	s_waitcnt lgkmcnt(2)
	v_mfma_f32_16x16x32_bf16 v[62:65], v[34:37], v[244:247], v[62:65]
	s_waitcnt lgkmcnt(1)
	v_mfma_f32_16x16x32_bf16 v[62:65], v[30:33], v[252:255], v[62:65]
	s_waitcnt lgkmcnt(0)
	v_mfma_f32_16x16x32_bf16 v[62:65], v[26:29], v[58:61], v[62:65]
; #define MFMA16(a, b, c) __builtin_amdgcn_mfma_f32_16x16x32_bf16((a), (b), (c), 0, 0, 0)
; __device__ void mlstm2_phase(const Params& p, unsigned char* smem) {
;     ...
;             { f32x4 accS[8];
; #pragma unroll
;               for (int n = 0; n < 8; ++n) { accS[n] = (f32x4){0.f, 0.f, 0.f, 0.f};
;                 if (n <= wave) {
; #pragma unroll
;                     for (int ks = 0; ks < 8; ++ks) { const bf16x8 kf = *(const bf16x8*)(Ks + (16 * n + l15) * 264 + 32 * ks + 8 * lq); accS[n] = MFMA16(qf[ks], kf, accS[n]); } } }
.LBB0_437:
	s_nop 4
	v_cndmask_b32_e64 v58, 0, 1, s[92:93]
	v_cmp_ne_u32_e64 s[54:55], 1, v58
	s_andn2_b64 vcc, exec, s[92:93]
	v_mov_b32_e32 v74, 0
	v_mov_b32_e32 v75, 0
	v_mov_b32_e32 v76, 0
	v_mov_b32_e32 v77, 0
	s_cbranch_vccnz .LBB0_439
	ds_read_b128 v[240:243], v151 offset:33792
	ds_read_b128 v[244:247], v151 offset:33856
	ds_read_b128 v[252:255], v151 offset:33920
	ds_read_b128 v[58:61], v151 offset:33984
	s_waitcnt lgkmcnt(3)
	v_mfma_f32_16x16x32_bf16 v[74:77], v[54:57], v[240:243], 0
	ds_read_b128 v[240:243], v151 offset:34048
	s_waitcnt lgkmcnt(3)
	v_mfma_f32_16x16x32_bf16 v[74:77], v[50:53], v[244:247], v[74:77]
	ds_read_b128 v[244:247], v151 offset:34112
	s_waitcnt lgkmcnt(3)
	v_mfma_f32_16x16x32_bf16 v[74:77], v[46:49], v[252:255], v[74:77]
	ds_read_b128 v[252:255], v151 offset:34176
	s_waitcnt lgkmcnt(3)
	v_mfma_f32_16x16x32_bf16 v[74:77], v[42:45], v[58:61], v[74:77]
	ds_read_b128 v[58:61], v151 offset:34240
	s_waitcnt lgkmcnt(3)
	v_mfma_f32_16x16x32_bf16 v[74:77], v[38:41], v[240:243], v[74:77]
	s_waitcnt lgkmcnt(2)
	v_mfma_f32_16x16x32_bf16 v[74:77], v[34:37], v[244:247], v[74:77]
	s_waitcnt lgkmcnt(1)
	v_mfma_f32_16x16x32_bf16 v[74:77], v[30:33], v[252:255], v[74:77]
	s_waitcnt lgkmcnt(0)
	v_mfma_f32_16x16x32_bf16 v[74:77], v[26:29], v[58:61], v[74:77]
.LBB0_439:
	s_andn2_b64 vcc, exec, s[62:63]
	v_mov_b32_e32 v66, 0
	v_mov_b32_e32 v67, 0
	v_mov_b32_e32 v68, 0
	v_mov_b32_e32 v69, 0
	s_cbranch_vccnz .LBB0_441
	ds_read_b128 v[240:243], v151 offset:42240
	ds_read_b128 v[244:247], v151 offset:42304
	ds_read_b128 v[252:255], v151 offset:42368
	ds_read_b128 v[58:61], v151 offset:42432
	s_waitcnt lgkmcnt(3)
	v_mfma_f32_16x16x32_bf16 v[66:69], v[54:57], v[240:243], 0
	ds_read_b128 v[240:243], v151 offset:42496
	s_waitcnt lgkmcnt(3)
	v_mfma_f32_16x16x32_bf16 v[66:69], v[50:53], v[244:247], v[66:69]
	ds_read_b128 v[244:247], v151 offset:42560
	s_waitcnt lgkmcnt(3)
	v_mfma_f32_16x16x32_bf16 v[66:69], v[46:49], v[252:255], v[66:69]
	ds_read_b128 v[252:255], v151 offset:42624
	s_waitcnt lgkmcnt(3)
	v_mfma_f32_16x16x32_bf16 v[66:69], v[42:45], v[58:61], v[66:69]
	ds_read_b128 v[58:61], v151 offset:42688
	s_waitcnt lgkmcnt(3)
	v_mfma_f32_16x16x32_bf16 v[66:69], v[38:41], v[240:243], v[66:69]
	s_waitcnt lgkmcnt(2)
	v_mfma_f32_16x16x32_bf16 v[66:69], v[34:37], v[244:247], v[66:69]
	s_waitcnt lgkmcnt(1)
	v_mfma_f32_16x16x32_bf16 v[66:69], v[30:33], v[252:255], v[66:69]
	s_waitcnt lgkmcnt(0)
	v_mfma_f32_16x16x32_bf16 v[66:69], v[26:29], v[58:61], v[66:69]
.LBB0_441:
	s_nop 4
	v_cndmask_b32_e64 v59, 0, 1, s[58:59]
	s_nop 1
	v_cmp_ne_u32_e64 s[56:57], 1, v59
	s_andn2_b64 vcc, exec, s[58:59]
	v_mov_b32_e32 v70, 0
	v_mov_b32_e32 v71, 0
	v_mov_b32_e32 v72, 0
	v_mov_b32_e32 v73, 0
	s_cbranch_vccnz .LBB0_443
	ds_read_b128 v[240:243], v151 offset:50688
	ds_read_b128 v[244:247], v151 offset:50752
	ds_read_b128 v[252:255], v151 offset:50816
	ds_read_b128 v[58:61], v151 offset:50880
	s_waitcnt lgkmcnt(3)
	v_mfma_f32_16x16x32_bf16 v[70:73], v[54:57], v[240:243], 0
	ds_read_b128 v[240:243], v151 offset:50944
	s_waitcnt lgkmcnt(3)
	v_mfma_f32_16x16x32_bf16 v[70:73], v[50:53], v[244:247], v[70:73]
	ds_read_b128 v[244:247], v151 offset:51008
	s_waitcnt lgkmcnt(3)
	v_mfma_f32_16x16x32_bf16 v[70:73], v[46:49], v[252:255], v[70:73]
	ds_read_b128 v[252:255], v151 offset:51072
	s_waitcnt lgkmcnt(3)
	v_mfma_f32_16x16x32_bf16 v[70:73], v[42:45], v[58:61], v[70:73]
	ds_read_b128 v[58:61], v151 offset:51136
	s_waitcnt lgkmcnt(3)
	v_mfma_f32_16x16x32_bf16 v[70:73], v[38:41], v[240:243], v[70:73]
	s_waitcnt lgkmcnt(2)
	v_mfma_f32_16x16x32_bf16 v[70:73], v[34:37], v[244:247], v[70:73]
	s_waitcnt lgkmcnt(1)
	v_mfma_f32_16x16x32_bf16 v[70:73], v[30:33], v[252:255], v[70:73]
	s_waitcnt lgkmcnt(0)
	v_mfma_f32_16x16x32_bf16 v[70:73], v[26:29], v[58:61], v[70:73]
.LBB0_443:
	s_andn2_b64 vcc, exec, s[60:61]
	v_mov_b32_e32 v58, 0
	v_mov_b32_e32 v59, 0
	v_mov_b32_e32 v60, 0
	v_mov_b32_e32 v61, 0
	s_cbranch_vccnz .LBB0_445
	ds_read_b128 v[240:243], v151 offset:59136
	ds_read_b128 v[244:247], v151 offset:59200
	ds_read_b128 v[252:255], v151 offset:59264
	s_waitcnt lgkmcnt(2)
	v_mfma_f32_16x16x32_bf16 v[58:61], v[54:57], v[240:243], 0
	ds_read_b128 v[240:243], v151 offset:59328
	s_waitcnt lgkmcnt(2)
	v_mfma_f32_16x16x32_bf16 v[58:61], v[50:53], v[244:247], v[58:61]
	ds_read_b128 v[244:247], v151 offset:59392
	s_waitcnt lgkmcnt(2)
	v_mfma_f32_16x16x32_bf16 v[58:61], v[46:49], v[252:255], v[58:61]
	ds_read_b128 v[252:255], v151 offset:59456
	s_waitcnt lgkmcnt(2)
	v_mfma_f32_16x16x32_bf16 v[58:61], v[42:45], v[240:243], v[58:61]
	ds_read_b128 v[240:243], v151 offset:59520
	s_waitcnt lgkmcnt(2)
	v_mfma_f32_16x16x32_bf16 v[58:61], v[38:41], v[244:247], v[58:61]
	ds_read_b128 v[244:247], v151 offset:59584
	s_waitcnt lgkmcnt(2)
	v_mfma_f32_16x16x32_bf16 v[58:61], v[34:37], v[252:255], v[58:61]
	s_waitcnt lgkmcnt(1)
	v_mfma_f32_16x16x32_bf16 v[58:61], v[30:33], v[240:243], v[58:61]
	s_waitcnt lgkmcnt(0)
	v_mfma_f32_16x16x32_bf16 v[58:61], v[26:29], v[244:247], v[58:61]

; __global__ void __launch_bounds__(512, 2) mega(Params p) {
;     extern __shared__ __attribute__((aligned(16))) unsigned char smem[];
	.amdhsa_kernel _Z4mega6Params
		.amdhsa_group_segment_fixed_size 0
		.amdhsa_private_segment_fixed_size 0
		.amdhsa_kernarg_size 608
		.amdhsa_user_sgpr_count 2
		.amdhsa_user_sgpr_dispatch_ptr 0
		.amdhsa_user_sgpr_queue_ptr 0
		.amdhsa_user_sgpr_kernarg_segment_ptr 1
		.amdhsa_user_sgpr_dispatch_id 0
		.amdhsa_user_sgpr_kernarg_preload_length 0
		.amdhsa_user_sgpr_kernarg_preload_offset 0
		.amdhsa_user_sgpr_private_segment_size 0
		.amdhsa_uses_dynamic_stack 0
		.amdhsa_enable_private_segment 0
		.amdhsa_system_sgpr_workgroup_id_x 1
		.amdhsa_system_sgpr_workgroup_id_y 0
		.amdhsa_system_sgpr_workgroup_id_z 0
		.amdhsa_system_sgpr_workgroup_info 0
		.amdhsa_system_vgpr_workitem_id 2
		.amdhsa_next_free_vgpr 256
		.amdhsa_next_free_sgpr 102
		.amdhsa_accum_offset 256
		.amdhsa_reserve_vcc 1
		.amdhsa_float_round_mode_32 0
		.amdhsa_float_round_mode_16_64 0
		.amdhsa_float_denorm_mode_32 3
		.amdhsa_float_denorm_mode_16_64 3
		.amdhsa_dx10_clamp 1
		.amdhsa_ieee_mode 1
		.amdhsa_fp16_overflow 0
		.amdhsa_tg_split 0
		.amdhsa_exception_fp_ieee_invalid_op 0
		.amdhsa_exception_fp_denorm_src 0
		.amdhsa_exception_fp_ieee_div_zero 0
		.amdhsa_exception_fp_ieee_overflow 0
		.amdhsa_exception_fp_ieee_underflow 0
		.amdhsa_exception_fp_ieee_inexact 0
		.amdhsa_exception_int_div_zero 0
	.end_amdhsa_kernel

; __global__ void __launch_bounds__(512, 2) mega(Params p) {
;     extern __shared__ __attribute__((aligned(16))) unsigned char smem[];
amdhsa.kernels:
  - .agpr_count:     0
    .args:
      - .offset:         0
        .size:           352
        .value_kind:     by_value
      - .offset:         352
        .size:           4
        .value_kind:     hidden_block_count_x
      - .offset:         356
        .size:           4
        .value_kind:     hidden_block_count_y
      - .offset:         360
        .size:           4
        .value_kind:     hidden_block_count_z
      - .offset:         364
        .size:           2
        .value_kind:     hidden_group_size_x
      - .offset:         366
        .size:           2
        .value_kind:     hidden_group_size_y
      - .offset:         368
        .size:           2
        .value_kind:     hidden_group_size_z
      - .offset:         370
        .size:           2
        .value_kind:     hidden_remainder_x
      - .offset:         372
        .size:           2
        .value_kind:     hidden_remainder_y
      - .offset:         374
        .size:           2
        .value_kind:     hidden_remainder_z
      - .offset:         392
        .size:           8
        .value_kind:     hidden_global_offset_x
      - .offset:         400
        .size:           8
        .value_kind:     hidden_global_offset_y
      - .offset:         408
        .size:           8
        .value_kind:     hidden_global_offset_z
      - .offset:         416
        .size:           2
        .value_kind:     hidden_grid_dims
      - .offset:         440
        .size:           8
        .value_kind:     hidden_multigrid_sync_arg
      - .offset:         472
        .size:           4
        .value_kind:     hidden_dynamic_lds_size
    .group_segment_fixed_size: 0
    .kernarg_segment_align: 8
    .kernarg_segment_size: 608
    .language:       OpenCL C
    .language_version:
      - 2
      - 0
    .max_flat_workgroup_size: 512
    .name:           _Z4mega6Params
    .private_segment_fixed_size: 0
    .sgpr_count:     108
    .sgpr_spill_count: 152
    .symbol:         _Z4mega6Params.kd
    .uniform_work_group_size: 1
    .uses_dynamic_stack: false
    .vgpr_count:     256
    .vgpr_spill_count: 0
    .wavefront_size: 64
